# RG-LRU pass-1 task: the 34 conditional conv-window row loads are issued back to back and waited for once (was one full load->wait->shift round trip each)
# speedup vs baseline: 1.0206x; 1.0162x over previous
; #define LAS __attribute__((address_space(3)))
; #define LDX(tt) (((tt) >= 0 && (tt) < seqlen) ? bf1(xp[(size_t)(tt) * INP]) : 0.f)
; #define LDX(tt) (((tt) >= 0 && (tt) < seqlen) ? bf1(xp[(size_t)(tt) * INP]) : 0.f)
; template <bool PASS2> ...
;     const int fr = lane & 15, fq = lane >> 4;
;     const int blk = t & 3, c = (t >> 2) % NCH, b = (t >> 2) / NCH;
;     const int seqlen = c < 8 ? 256 : 2048, t0 = c < 8 ? c * 32 : (c - 8) * 32, rbase = c < 8 ? ML + b * 256 : b * 2048;
;     bf16x8 af[2][2];
;     if (!PASS2) {
;         const int ch = blk * 64 + lane;
;         const float w0 = convw[(l * 4 + 0) * 256 + ch], w1 = convw[(l * 4 + 1) * 256 + ch], w2 = convw[(l * 4 + 2) * 256 + ch], w3 = convw[(l * 4 + 3) * 256 + ch], cb = convb[l * 256 + ch];
;         const bf16_t* xp = P + (size_t)rbase * INP + OFF_LRU + ch;
;     ...
;         float xs[35];
; #pragma unroll
;         for (int s = 0; s < 35; ++s) xs[s] = LDX(t0 + s - 2);
.LBB0_429:
	s_mov_b64 s[40:41], s[72:73]
	v_mov_b32 v97, v194
	s_mov_b32 s33, 0x8000
	v_readfirstlane_b32 s24, v97
	s_ashr_i32 s1, s24, 6
	s_add_i32 s23, s1, s69
	s_lshl_b32 s1, s1, 14
	s_add_i32 s22, s1, 0
	s_cmpk_gt_i32 s23, 0x8ff
	v_and_b32_e32 v95, 63, v97
	s_cbranch_scc1 .LBB0_544
	s_ashr_i32 s36, s23, 2
	s_mul_hi_i32 s1, s36, 0x38e38e39
	s_lshr_b32 s4, s1, 31
	s_ashr_i32 s1, s1, 4
	s_add_i32 s1, s1, s4
	s_mul_i32 s4, s1, 0x48
	s_sub_i32 s4, s36, s4
	s_lshl_b32 s6, s4, 5
	s_lshl_b32 s5, s1, 8
	s_add_i32 s7, s6, 0xffffff00
	s_add_i32 s14, s5, 0x4000
	s_lshl_b32 s1, s1, 11
	s_cmp_lt_i32 s4, 8
	s_movk_i32 s4, 0x800
	s_cselect_b32 s5, 0x100, s4
	s_cselect_b32 s4, s6, s7
	s_cselect_b32 s1, s14, s1
	s_and_b32 s6, s24, 0xc0
	v_or_b32_e32 v9, s6, v95
	v_readlane_b32 s7, v254, 32
	v_readlane_b32 s44, v251, 24
	v_readlane_b32 s45, v251, 25
	v_or_b32_e32 v0, s7, v9
	v_readlane_b32 s46, v251, 26
	v_readlane_b32 s47, v251, 27
	v_readlane_b32 s48, v251, 28
	v_readlane_b32 s49, v251, 29
	v_readlane_b32 s50, v251, 30
	v_readlane_b32 s51, v251, 31
	v_readlane_b32 s52, v251, 32
	v_readlane_b32 s53, v251, 33
	v_readlane_b32 s54, v251, 34
	v_readlane_b32 s55, v251, 35
	v_readlane_b32 s56, v251, 36
	v_readlane_b32 s57, v251, 37
	v_readlane_b32 s58, v251, 38
	v_readlane_b32 s59, v251, 39
	v_readlane_b32 s14, v254, 21
	s_mul_hi_i32 s7, s1, 0x2200
	v_lshl_add_u64 v[2:3], v[0:1], 2, s[58:59]
	v_readlane_b32 s44, v251, 40
	global_load_dword v7, v[2:3], off
	global_load_dword v6, v[2:3], off offset:1024
	global_load_dword v5, v[2:3], off offset:2048
	global_load_dword v4, v[2:3], off offset:3072
	v_or_b32_e32 v0, s14, v9
	v_readlane_b32 s45, v251, 41
	s_mul_i32 s14, s1, 0x2200
	s_add_u32 s18, s40, s14
	v_lshl_add_u64 v[2:3], v[0:1], 2, s[44:45]
	global_load_dword v8, v[2:3], off
	s_addc_u32 s19, s41, s7
	v_lshlrev_b32_e32 v0, 1, v9
	s_cmp_lt_i32 s4, 2
	v_lshl_add_u64 v[2:3], s[18:19], 0, v[0:1]
	s_cselect_b64 s[18:19], -1, 0
	s_cmp_le_i32 s4, s5
	s_cselect_b64 s[20:21], -1, 0
	s_cmp_gt_i32 s4, s5
	v_readlane_b32 s15, v254, 22
	s_cselect_b64 s[26:27], -1, 0
	s_mov_b64 s[14:15], 0x8eb8340
	s_or_b64 s[18:19], s[18:19], s[26:27]
	v_lshl_add_u64 v[2:3], v[2:3], 0, s[14:15]
	v_mov_b32_e32 v0, 0
	s_and_b64 vcc, exec, s[18:19]
	v_mov_b32_e32 v9, 0
	v_readlane_b32 s46, v251, 42
	v_readlane_b32 s47, v251, 43
	v_readlane_b32 s48, v251, 44
	v_readlane_b32 s49, v251, 45
	v_readlane_b32 s50, v251, 46
	v_readlane_b32 s51, v251, 47
	v_readlane_b32 s52, v251, 48
	v_readlane_b32 s53, v251, 49
	v_readlane_b32 s54, v251, 50
	v_readlane_b32 s55, v251, 51
	v_readlane_b32 s56, v251, 52
	v_readlane_b32 s57, v251, 53
	v_readlane_b32 s58, v251, 54
	v_readlane_b32 s59, v251, 55
	s_cbranch_vccnz .LBB0_432
	s_add_i32 s7, s4, -2
	v_mad_u64_u32 v[14:15], s[18:19], s7, v202, v[2:3]
	flat_load_ushort v9, v[14:15]
	s_nop 0
	s_nop 0
.LBB0_432:
	s_cmp_lt_i32 s4, 1
	s_cselect_b64 s[18:19], -1, 0
	s_xor_b64 s[20:21], s[20:21], -1
	s_or_b64 s[18:19], s[18:19], s[20:21]
	s_and_b64 vcc, exec, s[18:19]
	s_cbranch_vccnz .LBB0_434
	s_add_i32 s7, s4, -1
	v_mad_u64_u32 v[14:15], s[18:19], s7, v202, v[2:3]
	flat_load_ushort v0, v[14:15]
	s_nop 0
	s_nop 0
.LBB0_434:
	v_mov_b32_e32 v14, 0
	s_cmp_ge_u32 s4, s5
	v_mov_b32_e32 v15, 0
	s_cbranch_scc1 .LBB0_436
	v_mad_u64_u32 v[16:17], s[18:19], s4, v202, v[2:3]
	flat_load_ushort v15, v[16:17]
	s_nop 0
	s_nop 0
.LBB0_436:
	s_or_b32 s7, s4, 1
	s_cmp_gt_i32 s4, -1
	s_cselect_b64 s[20:21], -1, 0
	s_cmp_lt_i32 s7, s5
	s_cselect_b64 s[18:19], -1, 0
	s_and_b64 s[18:19], s[20:21], s[18:19]
	s_andn2_b64 vcc, exec, s[18:19]
	s_cbranch_vccnz .LBB0_438
	v_mad_u64_u32 v[16:17], s[18:19], s7, v202, v[2:3]
	flat_load_ushort v14, v[16:17]
	s_nop 0
	s_nop 0
.LBB0_438:
	s_or_b32 s7, s4, 2
	s_cmp_lt_i32 s7, s5
	s_cselect_b64 s[18:19], -1, 0
	s_and_b64 s[18:19], s[20:21], s[18:19]
	v_mov_b32_e32 v16, 0
	s_andn2_b64 vcc, exec, s[18:19]
	v_mov_b32_e32 v17, 0
	s_cbranch_vccnz .LBB0_440
	v_mad_u64_u32 v[18:19], s[18:19], s7, v202, v[2:3]
	flat_load_ushort v17, v[18:19]
	s_nop 0
	s_nop 0
.LBB0_440:
	s_or_b32 s7, s4, 3
	s_cmp_lt_i32 s7, s5
	s_cselect_b64 s[18:19], -1, 0
	s_and_b64 s[18:19], s[20:21], s[18:19]
	s_andn2_b64 vcc, exec, s[18:19]
	s_cbranch_vccnz .LBB0_442
	v_mad_u64_u32 v[18:19], s[18:19], s7, v202, v[2:3]
	flat_load_ushort v16, v[18:19]
	s_nop 0
	s_nop 0
.LBB0_442:
	s_or_b32 s7, s4, 4
	s_cmp_lt_i32 s7, s5
	s_cselect_b64 s[18:19], -1, 0
	s_and_b64 s[18:19], s[20:21], s[18:19]
	v_mov_b32_e32 v18, 0
	s_andn2_b64 vcc, exec, s[18:19]
	v_mov_b32_e32 v19, 0
	s_cbranch_vccnz .LBB0_444
	v_mad_u64_u32 v[20:21], s[18:19], s7, v202, v[2:3]
	flat_load_ushort v19, v[20:21]
	s_nop 0
	s_nop 0
.LBB0_444:
	s_or_b32 s7, s4, 5
	s_cmp_lt_i32 s7, s5
	s_cselect_b64 s[18:19], -1, 0
	s_and_b64 s[18:19], s[20:21], s[18:19]
	s_andn2_b64 vcc, exec, s[18:19]
	s_cbranch_vccnz .LBB0_446
	v_mad_u64_u32 v[20:21], s[18:19], s7, v202, v[2:3]
	flat_load_ushort v18, v[20:21]
	s_nop 0
	s_nop 0
.LBB0_446:
	s_or_b32 s7, s4, 6
	s_cmp_lt_i32 s7, s5
	s_cselect_b64 s[18:19], -1, 0
	s_and_b64 s[18:19], s[20:21], s[18:19]
	v_mov_b32_e32 v20, 0
	s_andn2_b64 vcc, exec, s[18:19]
	v_mov_b32_e32 v21, 0
	s_cbranch_vccnz .LBB0_448
	v_mad_u64_u32 v[22:23], s[18:19], s7, v202, v[2:3]
	flat_load_ushort v21, v[22:23]
	s_nop 0
	s_nop 0
.LBB0_448:
	s_or_b32 s7, s4, 7
	s_cmp_lt_i32 s7, s5
	s_cselect_b64 s[18:19], -1, 0
	s_and_b64 s[18:19], s[20:21], s[18:19]
	s_andn2_b64 vcc, exec, s[18:19]
	s_cbranch_vccnz .LBB0_450
	v_mad_u64_u32 v[22:23], s[18:19], s7, v202, v[2:3]
	flat_load_ushort v20, v[22:23]
	s_nop 0
	s_nop 0
; #define LDX(tt) (((tt) >= 0 && (tt) < seqlen) ? bf1(xp[(size_t)(tt) * INP]) : 0.f)
; #define LDX(tt) (((tt) >= 0 && (tt) < seqlen) ? bf1(xp[(size_t)(tt) * INP]) : 0.f)
; template <bool PASS2> ...
;     ...
;         float xs[35];
; #pragma unroll
;         for (int s = 0; s < 35; ++s) xs[s] = LDX(t0 + s - 2);
.LBB0_450:
	s_or_b32 s7, s4, 8
	s_cmp_lt_i32 s7, s5
	s_cselect_b64 s[18:19], -1, 0
	s_and_b64 s[18:19], s[20:21], s[18:19]
	v_mov_b32_e32 v22, 0
	s_andn2_b64 vcc, exec, s[18:19]
	v_mov_b32_e32 v23, 0
	s_cbranch_vccnz .LBB0_452
	v_mad_u64_u32 v[24:25], s[18:19], s7, v202, v[2:3]
	flat_load_ushort v23, v[24:25]
	s_nop 0
	s_nop 0
.LBB0_452:
	s_or_b32 s7, s4, 9
	s_cmp_lt_i32 s7, s5
	s_cselect_b64 s[18:19], -1, 0
	s_and_b64 s[18:19], s[20:21], s[18:19]
	s_andn2_b64 vcc, exec, s[18:19]
	s_cbranch_vccnz .LBB0_454
	v_mad_u64_u32 v[24:25], s[18:19], s7, v202, v[2:3]
	flat_load_ushort v22, v[24:25]
	s_nop 0
	s_nop 0
.LBB0_454:
	s_or_b32 s7, s4, 10
	s_cmp_lt_i32 s7, s5
	s_cselect_b64 s[18:19], -1, 0
	s_and_b64 s[18:19], s[20:21], s[18:19]
	v_mov_b32_e32 v24, 0
	s_andn2_b64 vcc, exec, s[18:19]
	v_mov_b32_e32 v25, 0
	s_cbranch_vccnz .LBB0_456
	v_mad_u64_u32 v[26:27], s[18:19], s7, v202, v[2:3]
	flat_load_ushort v25, v[26:27]
	s_nop 0
	s_nop 0
.LBB0_456:
	s_or_b32 s7, s4, 11
	s_cmp_lt_i32 s7, s5
	s_cselect_b64 s[18:19], -1, 0
	s_and_b64 s[18:19], s[20:21], s[18:19]
	s_andn2_b64 vcc, exec, s[18:19]
	s_cbranch_vccnz .LBB0_458
	v_mad_u64_u32 v[26:27], s[18:19], s7, v202, v[2:3]
	flat_load_ushort v24, v[26:27]
	s_nop 0
	s_nop 0
.LBB0_458:
	s_or_b32 s7, s4, 12
	s_cmp_lt_i32 s7, s5
	s_cselect_b64 s[18:19], -1, 0
	s_and_b64 s[18:19], s[20:21], s[18:19]
	v_mov_b32_e32 v26, 0
	s_andn2_b64 vcc, exec, s[18:19]
	v_mov_b32_e32 v27, 0
	s_cbranch_vccnz .LBB0_460
	v_mad_u64_u32 v[28:29], s[18:19], s7, v202, v[2:3]
	flat_load_ushort v27, v[28:29]
	s_nop 0
	s_nop 0
.LBB0_460:
	s_or_b32 s7, s4, 13
	s_cmp_lt_i32 s7, s5
	s_cselect_b64 s[18:19], -1, 0
	s_and_b64 s[18:19], s[20:21], s[18:19]
	s_andn2_b64 vcc, exec, s[18:19]
	s_cbranch_vccnz .LBB0_462
	v_mad_u64_u32 v[28:29], s[18:19], s7, v202, v[2:3]
	flat_load_ushort v26, v[28:29]
	s_nop 0
	s_nop 0
.LBB0_462:
	s_or_b32 s7, s4, 14
	s_cmp_lt_i32 s7, s5
	s_cselect_b64 s[18:19], -1, 0
	s_and_b64 s[18:19], s[20:21], s[18:19]
	v_mov_b32_e32 v28, 0
	s_andn2_b64 vcc, exec, s[18:19]
	v_mov_b32_e32 v29, 0
	s_cbranch_vccnz .LBB0_464
	v_mad_u64_u32 v[30:31], s[18:19], s7, v202, v[2:3]
	flat_load_ushort v29, v[30:31]
	s_nop 0
	s_nop 0
.LBB0_464:
	s_or_b32 s7, s4, 15
	s_cmp_lt_i32 s7, s5
	s_cselect_b64 s[18:19], -1, 0
	s_and_b64 s[18:19], s[20:21], s[18:19]
	s_andn2_b64 vcc, exec, s[18:19]
	s_cbranch_vccnz .LBB0_466
	v_mad_u64_u32 v[30:31], s[18:19], s7, v202, v[2:3]
	flat_load_ushort v28, v[30:31]
	s_nop 0
	s_nop 0
.LBB0_466:
	s_or_b32 s7, s4, 16
	s_cmp_lt_i32 s7, s5
	s_cselect_b64 s[18:19], -1, 0
	s_and_b64 s[18:19], s[20:21], s[18:19]
	v_mov_b32_e32 v30, 0
	s_andn2_b64 vcc, exec, s[18:19]
	v_mov_b32_e32 v31, 0
	s_cbranch_vccnz .LBB0_468
	v_mad_u64_u32 v[32:33], s[18:19], s7, v202, v[2:3]
	flat_load_ushort v31, v[32:33]
	s_nop 0
	s_nop 0
.LBB0_468:
	s_or_b32 s7, s4, 17
	s_cmp_lt_i32 s7, s5
	s_cselect_b64 s[18:19], -1, 0
	s_and_b64 s[18:19], s[20:21], s[18:19]
	s_andn2_b64 vcc, exec, s[18:19]
	s_cbranch_vccnz .LBB0_470
	v_mad_u64_u32 v[32:33], s[18:19], s7, v202, v[2:3]
	flat_load_ushort v30, v[32:33]
	s_nop 0
	s_nop 0
.LBB0_470:
	s_or_b32 s7, s4, 18
	s_cmp_lt_i32 s7, s5
	s_cselect_b64 s[18:19], -1, 0
	s_and_b64 s[18:19], s[20:21], s[18:19]
	v_mov_b32_e32 v32, 0
	s_andn2_b64 vcc, exec, s[18:19]
	v_mov_b32_e32 v33, 0
	s_cbranch_vccnz .LBB0_472
	v_mad_u64_u32 v[34:35], s[18:19], s7, v202, v[2:3]
	flat_load_ushort v33, v[34:35]
	s_nop 0
	s_nop 0
.LBB0_472:
	s_or_b32 s7, s4, 19
	s_cmp_lt_i32 s7, s5
	s_cselect_b64 s[18:19], -1, 0
	s_and_b64 s[18:19], s[20:21], s[18:19]
	s_andn2_b64 vcc, exec, s[18:19]
	s_cbranch_vccnz .LBB0_474
	v_mad_u64_u32 v[34:35], s[18:19], s7, v202, v[2:3]
	flat_load_ushort v32, v[34:35]
	s_nop 0
	s_nop 0
.LBB0_474:
	s_or_b32 s7, s4, 20
	s_cmp_lt_i32 s7, s5
	s_cselect_b64 s[18:19], -1, 0
	s_and_b64 s[18:19], s[20:21], s[18:19]
	v_mov_b32_e32 v34, 0
	s_andn2_b64 vcc, exec, s[18:19]
	v_mov_b32_e32 v35, 0
	s_cbranch_vccnz .LBB0_476
	v_mad_u64_u32 v[36:37], s[18:19], s7, v202, v[2:3]
	flat_load_ushort v35, v[36:37]
	s_nop 0
	s_nop 0
.LBB0_476:
	s_or_b32 s7, s4, 21
	s_cmp_lt_i32 s7, s5
	s_cselect_b64 s[18:19], -1, 0
	s_and_b64 s[18:19], s[20:21], s[18:19]
	s_andn2_b64 vcc, exec, s[18:19]
	s_cbranch_vccnz .LBB0_478
	v_mad_u64_u32 v[36:37], s[18:19], s7, v202, v[2:3]
	flat_load_ushort v34, v[36:37]
	s_nop 0
	s_nop 0
.LBB0_478:
	s_or_b32 s7, s4, 22
	s_cmp_lt_i32 s7, s5
	s_cselect_b64 s[18:19], -1, 0
	s_and_b64 s[18:19], s[20:21], s[18:19]
	v_mov_b32_e32 v36, 0
	s_andn2_b64 vcc, exec, s[18:19]
	v_mov_b32_e32 v37, 0
	s_cbranch_vccnz .LBB0_480
	v_mad_u64_u32 v[38:39], s[18:19], s7, v202, v[2:3]
	flat_load_ushort v37, v[38:39]
	s_nop 0
	s_nop 0
; #define LDX(tt) (((tt) >= 0 && (tt) < seqlen) ? bf1(xp[(size_t)(tt) * INP]) : 0.f)
; #define LDX(tt) (((tt) >= 0 && (tt) < seqlen) ? bf1(xp[(size_t)(tt) * INP]) : 0.f)
; template <bool PASS2> ...
;     ...
;         float xs[35];
; #pragma unroll
;         for (int s = 0; s < 35; ++s) xs[s] = LDX(t0 + s - 2);
.LBB0_480:
	s_or_b32 s7, s4, 23
	s_cmp_lt_i32 s7, s5
	s_cselect_b64 s[18:19], -1, 0
	s_and_b64 s[18:19], s[20:21], s[18:19]
	s_andn2_b64 vcc, exec, s[18:19]
	s_cbranch_vccnz .LBB0_482
	v_mad_u64_u32 v[38:39], s[18:19], s7, v202, v[2:3]
	flat_load_ushort v36, v[38:39]
	s_nop 0
	s_nop 0
.LBB0_482:
	s_or_b32 s7, s4, 24
	s_cmp_lt_i32 s7, s5
	s_cselect_b64 s[18:19], -1, 0
	s_and_b64 s[18:19], s[20:21], s[18:19]
	v_mov_b32_e32 v38, 0
	s_andn2_b64 vcc, exec, s[18:19]
	v_mov_b32_e32 v39, 0
	s_cbranch_vccnz .LBB0_484
	v_mad_u64_u32 v[40:41], s[18:19], s7, v202, v[2:3]
	flat_load_ushort v39, v[40:41]
	s_nop 0
	s_nop 0
.LBB0_484:
	s_or_b32 s7, s4, 25
	s_cmp_lt_i32 s7, s5
	s_cselect_b64 s[18:19], -1, 0
	s_and_b64 s[18:19], s[20:21], s[18:19]
	s_andn2_b64 vcc, exec, s[18:19]
	s_cbranch_vccnz .LBB0_486
	v_mad_u64_u32 v[40:41], s[18:19], s7, v202, v[2:3]
	flat_load_ushort v38, v[40:41]
	s_nop 0
	s_nop 0
.LBB0_486:
	s_or_b32 s7, s4, 26
	s_cmp_lt_i32 s7, s5
	s_cselect_b64 s[18:19], -1, 0
	s_and_b64 s[18:19], s[20:21], s[18:19]
	v_mov_b32_e32 v40, 0
	s_andn2_b64 vcc, exec, s[18:19]
	v_mov_b32_e32 v41, 0
	s_cbranch_vccnz .LBB0_488
	v_mad_u64_u32 v[42:43], s[18:19], s7, v202, v[2:3]
	flat_load_ushort v41, v[42:43]
	s_nop 0
	s_nop 0
.LBB0_488:
	s_or_b32 s7, s4, 27
	s_cmp_lt_i32 s7, s5
	s_cselect_b64 s[18:19], -1, 0
	s_and_b64 s[18:19], s[20:21], s[18:19]
	s_andn2_b64 vcc, exec, s[18:19]
	s_cbranch_vccnz .LBB0_490
	v_mad_u64_u32 v[42:43], s[18:19], s7, v202, v[2:3]
	flat_load_ushort v40, v[42:43]
	s_nop 0
	s_nop 0
.LBB0_490:
	s_or_b32 s7, s4, 28
	s_cmp_lt_i32 s7, s5
	s_cselect_b64 s[18:19], -1, 0
	s_and_b64 s[18:19], s[20:21], s[18:19]
	v_mov_b32_e32 v42, 0
	s_andn2_b64 vcc, exec, s[18:19]
	v_mov_b32_e32 v43, 0
	s_cbranch_vccnz .LBB0_492
	v_mad_u64_u32 v[44:45], s[18:19], s7, v202, v[2:3]
	flat_load_ushort v43, v[44:45]
	s_nop 0
	s_nop 0
.LBB0_492:
	s_or_b32 s7, s4, 29
	s_cmp_lt_i32 s7, s5
	s_cselect_b64 s[18:19], -1, 0
	s_and_b64 s[18:19], s[20:21], s[18:19]
	s_andn2_b64 vcc, exec, s[18:19]
	s_cbranch_vccnz .LBB0_494
	v_mad_u64_u32 v[44:45], s[18:19], s7, v202, v[2:3]
	flat_load_ushort v42, v[44:45]
	s_nop 0
	s_nop 0
.LBB0_494:
	s_or_b32 s7, s4, 30
	s_cmpk_gt_i32 s4, 0xffe1
	s_cselect_b64 s[18:19], -1, 0
	s_cmp_lt_i32 s7, s5
	s_cselect_b64 s[20:21], -1, 0
	s_and_b64 s[18:19], s[18:19], s[20:21]
	v_mov_b32_e32 v44, 0
	s_andn2_b64 vcc, exec, s[18:19]
	v_mov_b32_e32 v45, 0
	s_cbranch_vccnz .LBB0_496
	v_mad_u64_u32 v[46:47], s[18:19], s7, v202, v[2:3]
	flat_load_ushort v45, v[46:47]
	s_nop 0
	s_nop 0
.LBB0_496:
	s_or_b32 s7, s4, 31
	s_cmpk_gt_i32 s4, 0xffe0
	s_cselect_b64 s[18:19], -1, 0
	s_cmp_lt_i32 s7, s5
	s_cselect_b64 s[20:21], -1, 0
	s_and_b64 s[18:19], s[18:19], s[20:21]
	s_andn2_b64 vcc, exec, s[18:19]
	s_cbranch_vccnz .LBB0_498
	v_mad_u64_u32 v[46:47], s[18:19], s7, v202, v[2:3]
	flat_load_ushort v44, v[46:47]
	s_nop 0
	s_nop 0
.LBB0_498:
	s_waitcnt vmcnt(0) lgkmcnt(0)
	v_lshlrev_b32_e32 v9, 16, v9
	v_lshlrev_b32_e32 v0, 16, v0
	v_lshlrev_b32_e32 v15, 16, v15
	v_lshlrev_b32_e32 v14, 16, v14
	v_lshlrev_b32_e32 v17, 16, v17
	v_lshlrev_b32_e32 v16, 16, v16
	v_lshlrev_b32_e32 v19, 16, v19
	v_lshlrev_b32_e32 v18, 16, v18
	v_lshlrev_b32_e32 v21, 16, v21
	v_lshlrev_b32_e32 v20, 16, v20
	v_lshlrev_b32_e32 v23, 16, v23
	v_lshlrev_b32_e32 v22, 16, v22
	v_lshlrev_b32_e32 v25, 16, v25
	v_lshlrev_b32_e32 v24, 16, v24
	v_lshlrev_b32_e32 v27, 16, v27
	v_lshlrev_b32_e32 v26, 16, v26
	v_lshlrev_b32_e32 v29, 16, v29
	v_lshlrev_b32_e32 v28, 16, v28
	v_lshlrev_b32_e32 v31, 16, v31
	v_lshlrev_b32_e32 v30, 16, v30
	v_lshlrev_b32_e32 v33, 16, v33
	v_lshlrev_b32_e32 v32, 16, v32
	v_lshlrev_b32_e32 v35, 16, v35
	v_lshlrev_b32_e32 v34, 16, v34
	v_lshlrev_b32_e32 v37, 16, v37
	v_lshlrev_b32_e32 v36, 16, v36
	v_lshlrev_b32_e32 v39, 16, v39
	v_lshlrev_b32_e32 v38, 16, v38
	v_lshlrev_b32_e32 v41, 16, v41
	v_lshlrev_b32_e32 v40, 16, v40
	v_lshlrev_b32_e32 v43, 16, v43
	v_lshlrev_b32_e32 v42, 16, v42
	v_lshlrev_b32_e32 v45, 16, v45
	v_lshlrev_b32_e32 v44, 16, v44
	s_nop 0
	s_nop 0
	s_nop 0
	s_nop 0
	s_nop 0
	s_nop 0
	s_nop 0
	s_nop 0
	s_nop 0
	s_nop 0
	s_nop 0
	s_nop 0
	s_nop 0
	s_add_i32 s7, s4, 32
	s_cmpk_gt_i32 s4, 0xffdf
	s_cselect_b64 s[18:19], -1, 0
	s_cmp_lt_i32 s7, s5
	s_cselect_b64 s[20:21], -1, 0
	s_and_b64 s[18:19], s[18:19], s[20:21]
	s_andn2_b64 vcc, exec, s[18:19]
	v_mov_b32_e32 v46, 0
	s_cbranch_vccnz .LBB0_500
	v_mad_u64_u32 v[2:3], s[18:19], s7, v202, v[2:3]
	flat_load_ushort v2, v[2:3]
	s_waitcnt vmcnt(0) lgkmcnt(0)
	v_lshlrev_b32_e32 v46, 16, v2

; #define LAS __attribute__((address_space(3)))
; #define LDX(tt) (((tt) >= 0 && (tt) < seqlen) ? bf1(xp[(size_t)(tt) * INP]) : 0.f)
; #define LDX(tt) (((tt) >= 0 && (tt) < seqlen) ? bf1(xp[(size_t)(tt) * INP]) : 0.f)
; template <bool PASS2> ...
;     const int fr = lane & 15, fq = lane >> 4;
;     const int blk = t & 3, c = (t >> 2) % NCH, b = (t >> 2) / NCH;
;     const int seqlen = c < 8 ? 256 : 2048, t0 = c < 8 ? c * 32 : (c - 8) * 32, rbase = c < 8 ? ML + b * 256 : b * 2048;
;     bf16x8 af[2][2];
;     if (!PASS2) {
;         const int ch = blk * 64 + lane;
;         const float w0 = convw[(l * 4 + 0) * 256 + ch], w1 = convw[(l * 4 + 1) * 256 + ch], w2 = convw[(l * 4 + 2) * 256 + ch], w3 = convw[(l * 4 + 3) * 256 + ch], cb = convb[l * 256 + ch];
;         const bf16_t* xp = P + (size_t)rbase * INP + OFF_LRU + ch;
;     ...
;         float xs[35];
; #pragma unroll
;         for (int s = 0; s < 35; ++s) xs[s] = LDX(t0 + s - 2);
.LBB0_548:
	s_ashr_i32 s4, s1, 2
	s_mov_b32 s25, s1
	s_mul_hi_i32 s1, s4, 0x38e38e39
	s_lshr_b32 s6, s1, 31
	s_ashr_i32 s1, s1, 4
	s_add_i32 s1, s1, s6
	s_mul_i32 s6, s1, 0x48
	s_sub_i32 s6, s4, s6
	s_lshl_b32 s7, s6, 5
	s_lshl_b32 s15, s1, 8
	s_add_i32 s14, s7, 0xffffff00
	s_addk_i32 s15, 0x4000
	s_lshl_b32 s1, s1, 11
	s_cmp_lt_i32 s6, 8
	s_movk_i32 s6, 0x800
	s_cselect_b32 s6, 0x100, s6
	s_cselect_b32 s38, s7, s14
	s_cselect_b32 s1, s15, s1
	s_lshl_b32 s5, s5, 6
	s_and_b32 s5, s5, 0xc0
	v_or_b32_e32 v9, s5, v95
	v_readlane_b32 s7, v254, 32
	v_readlane_b32 s48, v251, 24
	v_readlane_b32 s49, v251, 25
	s_waitcnt lgkmcnt(0)
	v_or_b32_e32 v0, s7, v9
	v_readlane_b32 s50, v251, 26
	v_readlane_b32 s51, v251, 27
	v_readlane_b32 s52, v251, 28
	v_readlane_b32 s53, v251, 29
	v_readlane_b32 s54, v251, 30
	v_readlane_b32 s55, v251, 31
	v_readlane_b32 s56, v251, 32
	v_readlane_b32 s57, v251, 33
	v_readlane_b32 s58, v251, 34
	v_readlane_b32 s59, v251, 35
	v_readlane_b32 s60, v251, 36
	v_readlane_b32 s61, v251, 37
	v_readlane_b32 s62, v251, 38
	v_readlane_b32 s63, v251, 39
	v_readlane_b32 s14, v254, 21
	s_mul_hi_i32 s7, s1, 0x2200
	v_lshl_add_u64 v[2:3], v[0:1], 2, s[62:63]
	v_readlane_b32 s48, v251, 40
	global_load_dword v7, v[2:3], off
	global_load_dword v6, v[2:3], off offset:1024
	global_load_dword v5, v[2:3], off offset:2048
	global_load_dword v4, v[2:3], off offset:3072
	v_or_b32_e32 v0, s14, v9
	v_readlane_b32 s49, v251, 41
	s_mul_i32 s14, s1, 0x2200
	s_add_u32 s18, s40, s14
	v_lshl_add_u64 v[2:3], v[0:1], 2, s[48:49]
	global_load_dword v8, v[2:3], off
	s_addc_u32 s19, s41, s7
	v_lshlrev_b32_e32 v0, 1, v9
	s_cmp_lt_i32 s38, 2
	v_lshl_add_u64 v[2:3], s[18:19], 0, v[0:1]
	s_cselect_b64 s[18:19], -1, 0
	s_cmp_le_i32 s38, s6
	s_cselect_b64 s[20:21], -1, 0
	s_cmp_gt_i32 s38, s6
	v_readlane_b32 s15, v254, 22
	s_cselect_b64 s[26:27], -1, 0
	s_mov_b64 s[14:15], 0x8eb8340
	s_or_b64 s[18:19], s[18:19], s[26:27]
	v_lshl_add_u64 v[2:3], v[2:3], 0, s[14:15]
	v_mov_b32_e32 v0, 0
	s_and_b64 vcc, exec, s[18:19]
	v_mov_b32_e32 v9, 0
	v_readlane_b32 s50, v251, 42
	v_readlane_b32 s51, v251, 43
	v_readlane_b32 s52, v251, 44
	v_readlane_b32 s53, v251, 45
	v_readlane_b32 s54, v251, 46
	v_readlane_b32 s55, v251, 47
	v_readlane_b32 s56, v251, 48
	v_readlane_b32 s57, v251, 49
	v_readlane_b32 s58, v251, 50
	v_readlane_b32 s59, v251, 51
	v_readlane_b32 s60, v251, 52
	v_readlane_b32 s61, v251, 53
	v_readlane_b32 s62, v251, 54
	v_readlane_b32 s63, v251, 55
	s_cbranch_vccnz .LBB0_550
	s_add_i32 s7, s38, -2
	v_mad_u64_u32 v[14:15], s[18:19], s7, v202, v[2:3]
	flat_load_ushort v9, v[14:15]
	s_nop 0
	s_nop 0
.LBB0_550:
	s_cmp_lt_i32 s38, 1
	s_cselect_b64 s[18:19], -1, 0
	s_xor_b64 s[20:21], s[20:21], -1
	s_or_b64 s[18:19], s[18:19], s[20:21]
	s_and_b64 vcc, exec, s[18:19]
	s_cbranch_vccnz .LBB0_552
	s_add_i32 s7, s38, -1
	v_mad_u64_u32 v[14:15], s[18:19], s7, v202, v[2:3]
	flat_load_ushort v0, v[14:15]
	s_nop 0
	s_nop 0
.LBB0_552:
	v_mov_b32_e32 v14, 0
	s_cmp_ge_u32 s38, s6
	v_mov_b32_e32 v15, 0
	s_cbranch_scc1 .LBB0_554
	v_mad_u64_u32 v[16:17], s[18:19], s38, v202, v[2:3]
	flat_load_ushort v15, v[16:17]
	s_nop 0
	s_nop 0
.LBB0_554:
	s_or_b32 s7, s38, 1
	s_cmp_gt_i32 s38, -1
	s_cselect_b64 s[20:21], -1, 0
	s_cmp_lt_i32 s7, s6
	s_cselect_b64 s[18:19], -1, 0
	s_and_b64 s[18:19], s[20:21], s[18:19]
	s_andn2_b64 vcc, exec, s[18:19]
	s_cbranch_vccnz .LBB0_556
	v_mad_u64_u32 v[16:17], s[18:19], s7, v202, v[2:3]
	flat_load_ushort v14, v[16:17]
	s_nop 0
	s_nop 0
.LBB0_556:
	s_or_b32 s7, s38, 2
	s_cmp_lt_i32 s7, s6
	s_cselect_b64 s[18:19], -1, 0
	s_and_b64 s[18:19], s[20:21], s[18:19]
	v_mov_b32_e32 v16, 0
	s_andn2_b64 vcc, exec, s[18:19]
	v_mov_b32_e32 v17, 0
	s_cbranch_vccnz .LBB0_558
	v_mad_u64_u32 v[18:19], s[18:19], s7, v202, v[2:3]
	flat_load_ushort v17, v[18:19]
	s_nop 0
	s_nop 0
.LBB0_558:
	s_or_b32 s7, s38, 3
	s_cmp_lt_i32 s7, s6
	s_cselect_b64 s[18:19], -1, 0
	s_and_b64 s[18:19], s[20:21], s[18:19]
	s_andn2_b64 vcc, exec, s[18:19]
	s_cbranch_vccnz .LBB0_560
	v_mad_u64_u32 v[18:19], s[18:19], s7, v202, v[2:3]
	flat_load_ushort v16, v[18:19]
	s_nop 0
	s_nop 0
.LBB0_560:
	s_or_b32 s7, s38, 4
	s_cmp_lt_i32 s7, s6
	s_cselect_b64 s[18:19], -1, 0
	s_and_b64 s[18:19], s[20:21], s[18:19]
	v_mov_b32_e32 v18, 0
	s_andn2_b64 vcc, exec, s[18:19]
	v_mov_b32_e32 v19, 0
	s_cbranch_vccnz .LBB0_562
	v_mad_u64_u32 v[20:21], s[18:19], s7, v202, v[2:3]
	flat_load_ushort v19, v[20:21]
	s_nop 0
	s_nop 0
.LBB0_562:
	s_or_b32 s7, s38, 5
	s_cmp_lt_i32 s7, s6
	s_cselect_b64 s[18:19], -1, 0
	s_and_b64 s[18:19], s[20:21], s[18:19]
	s_andn2_b64 vcc, exec, s[18:19]
	s_cbranch_vccnz .LBB0_564
	v_mad_u64_u32 v[20:21], s[18:19], s7, v202, v[2:3]
	flat_load_ushort v18, v[20:21]
	s_nop 0
	s_nop 0
.LBB0_564:
	s_or_b32 s7, s38, 6
	s_cmp_lt_i32 s7, s6
	s_cselect_b64 s[18:19], -1, 0
	s_and_b64 s[18:19], s[20:21], s[18:19]
	v_mov_b32_e32 v20, 0
	s_andn2_b64 vcc, exec, s[18:19]
	v_mov_b32_e32 v21, 0
	s_cbranch_vccnz .LBB0_566
	v_mad_u64_u32 v[22:23], s[18:19], s7, v202, v[2:3]
	flat_load_ushort v21, v[22:23]
	s_nop 0
	s_nop 0
.LBB0_566:
	s_or_b32 s7, s38, 7
	s_cmp_lt_i32 s7, s6
	s_cselect_b64 s[18:19], -1, 0
	s_and_b64 s[18:19], s[20:21], s[18:19]
	s_andn2_b64 vcc, exec, s[18:19]
	s_cbranch_vccnz .LBB0_568
	v_mad_u64_u32 v[22:23], s[18:19], s7, v202, v[2:3]
	flat_load_ushort v20, v[22:23]
	s_nop 0
	s_nop 0
.LBB0_568:
	s_or_b32 s7, s38, 8
	s_cmp_lt_i32 s7, s6
	s_cselect_b64 s[18:19], -1, 0
	s_and_b64 s[18:19], s[20:21], s[18:19]
	v_mov_b32_e32 v22, 0
	s_andn2_b64 vcc, exec, s[18:19]
	v_mov_b32_e32 v23, 0
	s_cbranch_vccnz .LBB0_570
	v_mad_u64_u32 v[24:25], s[18:19], s7, v202, v[2:3]
	flat_load_ushort v23, v[24:25]
	s_nop 0
	s_nop 0
; #define LDX(tt) (((tt) >= 0 && (tt) < seqlen) ? bf1(xp[(size_t)(tt) * INP]) : 0.f)
; #define LDX(tt) (((tt) >= 0 && (tt) < seqlen) ? bf1(xp[(size_t)(tt) * INP]) : 0.f)
; template <bool PASS2> ...
;     ...
;         float xs[35];
; #pragma unroll
;         for (int s = 0; s < 35; ++s) xs[s] = LDX(t0 + s - 2);
.LBB0_570:
	s_or_b32 s7, s38, 9
	s_cmp_lt_i32 s7, s6
	s_cselect_b64 s[18:19], -1, 0
	s_and_b64 s[18:19], s[20:21], s[18:19]
	s_andn2_b64 vcc, exec, s[18:19]
	s_cbranch_vccnz .LBB0_572
	v_mad_u64_u32 v[24:25], s[18:19], s7, v202, v[2:3]
	flat_load_ushort v22, v[24:25]
	s_nop 0
	s_nop 0
.LBB0_572:
	s_or_b32 s7, s38, 10
	s_cmp_lt_i32 s7, s6
	s_cselect_b64 s[18:19], -1, 0
	s_and_b64 s[18:19], s[20:21], s[18:19]
	v_mov_b32_e32 v24, 0
	s_andn2_b64 vcc, exec, s[18:19]
	v_mov_b32_e32 v25, 0
	s_cbranch_vccnz .LBB0_574
	v_mad_u64_u32 v[26:27], s[18:19], s7, v202, v[2:3]
	flat_load_ushort v25, v[26:27]
	s_nop 0
	s_nop 0
.LBB0_574:
	s_or_b32 s7, s38, 11
	s_cmp_lt_i32 s7, s6
	s_cselect_b64 s[18:19], -1, 0
	s_and_b64 s[18:19], s[20:21], s[18:19]
	s_andn2_b64 vcc, exec, s[18:19]
	s_cbranch_vccnz .LBB0_576
	v_mad_u64_u32 v[26:27], s[18:19], s7, v202, v[2:3]
	flat_load_ushort v24, v[26:27]
	s_nop 0
	s_nop 0
.LBB0_576:
	s_or_b32 s7, s38, 12
	s_cmp_lt_i32 s7, s6
	s_cselect_b64 s[18:19], -1, 0
	s_and_b64 s[18:19], s[20:21], s[18:19]
	v_mov_b32_e32 v26, 0
	s_andn2_b64 vcc, exec, s[18:19]
	v_mov_b32_e32 v27, 0
	s_cbranch_vccnz .LBB0_578
	v_mad_u64_u32 v[28:29], s[18:19], s7, v202, v[2:3]
	flat_load_ushort v27, v[28:29]
	s_nop 0
	s_nop 0
.LBB0_578:
	s_or_b32 s7, s38, 13
	s_cmp_lt_i32 s7, s6
	s_cselect_b64 s[18:19], -1, 0
	s_and_b64 s[18:19], s[20:21], s[18:19]
	s_andn2_b64 vcc, exec, s[18:19]
	s_cbranch_vccnz .LBB0_580
	v_mad_u64_u32 v[28:29], s[18:19], s7, v202, v[2:3]
	flat_load_ushort v26, v[28:29]
	s_nop 0
	s_nop 0
.LBB0_580:
	s_or_b32 s7, s38, 14
	s_cmp_lt_i32 s7, s6
	s_cselect_b64 s[18:19], -1, 0
	s_and_b64 s[18:19], s[20:21], s[18:19]
	v_mov_b32_e32 v28, 0
	s_andn2_b64 vcc, exec, s[18:19]
	v_mov_b32_e32 v29, 0
	s_cbranch_vccnz .LBB0_582
	v_mad_u64_u32 v[30:31], s[18:19], s7, v202, v[2:3]
	flat_load_ushort v29, v[30:31]
	s_nop 0
	s_nop 0
.LBB0_582:
	s_or_b32 s7, s38, 15
	s_cmp_lt_i32 s7, s6
	s_cselect_b64 s[18:19], -1, 0
	s_and_b64 s[18:19], s[20:21], s[18:19]
	s_andn2_b64 vcc, exec, s[18:19]
	s_cbranch_vccnz .LBB0_584
	v_mad_u64_u32 v[30:31], s[18:19], s7, v202, v[2:3]
	flat_load_ushort v28, v[30:31]
	s_nop 0
	s_nop 0
.LBB0_584:
	s_or_b32 s7, s38, 16
	s_cmp_lt_i32 s7, s6
	s_cselect_b64 s[18:19], -1, 0
	s_and_b64 s[18:19], s[20:21], s[18:19]
	v_mov_b32_e32 v30, 0
	s_andn2_b64 vcc, exec, s[18:19]
	v_mov_b32_e32 v31, 0
	s_cbranch_vccnz .LBB0_586
	v_mad_u64_u32 v[32:33], s[18:19], s7, v202, v[2:3]
	flat_load_ushort v31, v[32:33]
	s_nop 0
	s_nop 0
.LBB0_586:
	s_or_b32 s7, s38, 17
	s_cmp_lt_i32 s7, s6
	s_cselect_b64 s[18:19], -1, 0
	s_and_b64 s[18:19], s[20:21], s[18:19]
	s_andn2_b64 vcc, exec, s[18:19]
	s_cbranch_vccnz .LBB0_588
	v_mad_u64_u32 v[32:33], s[18:19], s7, v202, v[2:3]
	flat_load_ushort v30, v[32:33]
	s_nop 0
	s_nop 0
.LBB0_588:
	s_or_b32 s7, s38, 18
	s_cmp_lt_i32 s7, s6
	s_cselect_b64 s[18:19], -1, 0
	s_and_b64 s[18:19], s[20:21], s[18:19]
	v_mov_b32_e32 v32, 0
	s_andn2_b64 vcc, exec, s[18:19]
	v_mov_b32_e32 v33, 0
	s_cbranch_vccnz .LBB0_590
	v_mad_u64_u32 v[34:35], s[18:19], s7, v202, v[2:3]
	flat_load_ushort v33, v[34:35]
	s_nop 0
	s_nop 0
.LBB0_590:
	s_or_b32 s7, s38, 19
	s_cmp_lt_i32 s7, s6
	s_cselect_b64 s[18:19], -1, 0
	s_and_b64 s[18:19], s[20:21], s[18:19]
	s_andn2_b64 vcc, exec, s[18:19]
	s_cbranch_vccnz .LBB0_592
	v_mad_u64_u32 v[34:35], s[18:19], s7, v202, v[2:3]
	flat_load_ushort v32, v[34:35]
	s_nop 0
	s_nop 0
.LBB0_592:
	s_or_b32 s7, s38, 20
	s_cmp_lt_i32 s7, s6
	s_cselect_b64 s[18:19], -1, 0
	s_and_b64 s[18:19], s[20:21], s[18:19]
	v_mov_b32_e32 v34, 0
	s_andn2_b64 vcc, exec, s[18:19]
	v_mov_b32_e32 v35, 0
	s_cbranch_vccnz .LBB0_594
	v_mad_u64_u32 v[36:37], s[18:19], s7, v202, v[2:3]
	flat_load_ushort v35, v[36:37]
	s_nop 0
	s_nop 0
.LBB0_594:
	s_or_b32 s7, s38, 21
	s_cmp_lt_i32 s7, s6
	s_cselect_b64 s[18:19], -1, 0
	s_and_b64 s[18:19], s[20:21], s[18:19]
	s_andn2_b64 vcc, exec, s[18:19]
	s_cbranch_vccnz .LBB0_596
	v_mad_u64_u32 v[36:37], s[18:19], s7, v202, v[2:3]
	flat_load_ushort v34, v[36:37]
	s_nop 0
	s_nop 0
.LBB0_596:
	s_or_b32 s7, s38, 22
	s_cmp_lt_i32 s7, s6
	s_cselect_b64 s[18:19], -1, 0
	s_and_b64 s[18:19], s[20:21], s[18:19]
	v_mov_b32_e32 v36, 0
	s_andn2_b64 vcc, exec, s[18:19]
	v_mov_b32_e32 v37, 0
	s_cbranch_vccnz .LBB0_598
	v_mad_u64_u32 v[38:39], s[18:19], s7, v202, v[2:3]
	flat_load_ushort v37, v[38:39]
	s_nop 0
	s_nop 0
; #define LDX(tt) (((tt) >= 0 && (tt) < seqlen) ? bf1(xp[(size_t)(tt) * INP]) : 0.f)
; #define LDX(tt) (((tt) >= 0 && (tt) < seqlen) ? bf1(xp[(size_t)(tt) * INP]) : 0.f)
; template <bool PASS2> ...
;     ...
;         const int ch = blk * 64 + lane;
;         const float w0 = convw[(l * 4 + 0) * 256 + ch], w1 = convw[(l * 4 + 1) * 256 + ch], w2 = convw[(l * 4 + 2) * 256 + ch], w3 = convw[(l * 4 + 3) * 256 + ch], cb = convb[l * 256 + ch];
;         const bf16_t* xp = P + (size_t)rbase * INP + OFF_LRU + ch;
;     ...
;         float xs[35];
; #pragma unroll
;         for (int s = 0; s < 35; ++s) xs[s] = LDX(t0 + s - 2);
.LBB0_598:
	s_or_b32 s7, s38, 23
	s_cmp_lt_i32 s7, s6
	s_cselect_b64 s[18:19], -1, 0
	s_and_b64 s[18:19], s[20:21], s[18:19]
	s_andn2_b64 vcc, exec, s[18:19]
	s_cbranch_vccnz .LBB0_600
	v_mad_u64_u32 v[38:39], s[18:19], s7, v202, v[2:3]
	flat_load_ushort v36, v[38:39]
	s_nop 0
	s_nop 0
.LBB0_600:
	s_or_b32 s7, s38, 24
	s_cmp_lt_i32 s7, s6
	s_cselect_b64 s[18:19], -1, 0
	s_and_b64 s[18:19], s[20:21], s[18:19]
	v_mov_b32_e32 v38, 0
	s_andn2_b64 vcc, exec, s[18:19]
	v_mov_b32_e32 v39, 0
	s_cbranch_vccnz .LBB0_602
	v_mad_u64_u32 v[40:41], s[18:19], s7, v202, v[2:3]
	flat_load_ushort v39, v[40:41]
	s_nop 0
	s_nop 0
.LBB0_602:
	s_or_b32 s7, s38, 25
	s_cmp_lt_i32 s7, s6
	s_cselect_b64 s[18:19], -1, 0
	s_and_b64 s[18:19], s[20:21], s[18:19]
	s_andn2_b64 vcc, exec, s[18:19]
	s_cbranch_vccnz .LBB0_604
	v_mad_u64_u32 v[40:41], s[18:19], s7, v202, v[2:3]
	flat_load_ushort v38, v[40:41]
	s_nop 0
	s_nop 0
.LBB0_604:
	s_or_b32 s7, s38, 26
	s_cmp_lt_i32 s7, s6
	s_cselect_b64 s[18:19], -1, 0
	s_and_b64 s[18:19], s[20:21], s[18:19]
	v_mov_b32_e32 v40, 0
	s_andn2_b64 vcc, exec, s[18:19]
	v_mov_b32_e32 v41, 0
	s_cbranch_vccnz .LBB0_606
	v_mad_u64_u32 v[42:43], s[18:19], s7, v202, v[2:3]
	flat_load_ushort v41, v[42:43]
	s_nop 0
	s_nop 0
.LBB0_606:
	s_or_b32 s7, s38, 27
	s_cmp_lt_i32 s7, s6
	s_cselect_b64 s[18:19], -1, 0
	s_and_b64 s[18:19], s[20:21], s[18:19]
	s_andn2_b64 vcc, exec, s[18:19]
	s_cbranch_vccnz .LBB0_608
	v_mad_u64_u32 v[42:43], s[18:19], s7, v202, v[2:3]
	flat_load_ushort v40, v[42:43]
	s_nop 0
	s_nop 0
.LBB0_608:
	s_or_b32 s7, s38, 28
	s_cmp_lt_i32 s7, s6
	s_cselect_b64 s[18:19], -1, 0
	s_and_b64 s[18:19], s[20:21], s[18:19]
	v_mov_b32_e32 v42, 0
	s_andn2_b64 vcc, exec, s[18:19]
	v_mov_b32_e32 v43, 0
	s_cbranch_vccnz .LBB0_610
	v_mad_u64_u32 v[44:45], s[18:19], s7, v202, v[2:3]
	flat_load_ushort v43, v[44:45]
	s_nop 0
	s_nop 0
.LBB0_610:
	s_or_b32 s7, s38, 29
	s_cmp_lt_i32 s7, s6
	s_cselect_b64 s[18:19], -1, 0
	s_and_b64 s[18:19], s[20:21], s[18:19]
	s_andn2_b64 vcc, exec, s[18:19]
	s_cbranch_vccnz .LBB0_612
	v_mad_u64_u32 v[44:45], s[18:19], s7, v202, v[2:3]
	flat_load_ushort v42, v[44:45]
	s_nop 0
	s_nop 0
.LBB0_612:
	s_or_b32 s7, s38, 30
	s_cmpk_gt_i32 s38, 0xffe1
	s_cselect_b64 s[18:19], -1, 0
	s_cmp_lt_i32 s7, s6
	s_cselect_b64 s[20:21], -1, 0
	s_and_b64 s[18:19], s[18:19], s[20:21]
	v_mov_b32_e32 v44, 0
	s_andn2_b64 vcc, exec, s[18:19]
	v_mov_b32_e32 v45, 0
	s_cbranch_vccnz .LBB0_614
	v_mad_u64_u32 v[46:47], s[18:19], s7, v202, v[2:3]
	flat_load_ushort v45, v[46:47]
	s_nop 0
	s_nop 0
.LBB0_614:
	s_or_b32 s7, s38, 31
	s_cmpk_gt_i32 s38, 0xffe0
	s_cselect_b64 s[18:19], -1, 0
	s_cmp_lt_i32 s7, s6
	s_cselect_b64 s[20:21], -1, 0
	s_and_b64 s[18:19], s[18:19], s[20:21]
	s_andn2_b64 vcc, exec, s[18:19]
	s_cbranch_vccnz .LBB0_616
	v_mad_u64_u32 v[46:47], s[18:19], s7, v202, v[2:3]
	flat_load_ushort v44, v[46:47]
	s_nop 0
	s_nop 0
.LBB0_616:
	s_waitcnt vmcnt(0) lgkmcnt(0)
	v_lshlrev_b32_e32 v9, 16, v9
	v_lshlrev_b32_e32 v0, 16, v0
	v_lshlrev_b32_e32 v15, 16, v15
	v_lshlrev_b32_e32 v14, 16, v14
	v_lshlrev_b32_e32 v17, 16, v17
	v_lshlrev_b32_e32 v16, 16, v16
	v_lshlrev_b32_e32 v19, 16, v19
	v_lshlrev_b32_e32 v18, 16, v18
	v_lshlrev_b32_e32 v21, 16, v21
	v_lshlrev_b32_e32 v20, 16, v20
	v_lshlrev_b32_e32 v23, 16, v23
	v_lshlrev_b32_e32 v22, 16, v22
	v_lshlrev_b32_e32 v25, 16, v25
	v_lshlrev_b32_e32 v24, 16, v24
	v_lshlrev_b32_e32 v27, 16, v27
	v_lshlrev_b32_e32 v26, 16, v26
	v_lshlrev_b32_e32 v29, 16, v29
	v_lshlrev_b32_e32 v28, 16, v28
	v_lshlrev_b32_e32 v31, 16, v31
	v_lshlrev_b32_e32 v30, 16, v30
	v_lshlrev_b32_e32 v33, 16, v33
	v_lshlrev_b32_e32 v32, 16, v32
	v_lshlrev_b32_e32 v35, 16, v35
	v_lshlrev_b32_e32 v34, 16, v34
	v_lshlrev_b32_e32 v37, 16, v37
	v_lshlrev_b32_e32 v36, 16, v36
	v_lshlrev_b32_e32 v39, 16, v39
	v_lshlrev_b32_e32 v38, 16, v38
	v_lshlrev_b32_e32 v41, 16, v41
	v_lshlrev_b32_e32 v40, 16, v40
	v_lshlrev_b32_e32 v43, 16, v43
	v_lshlrev_b32_e32 v42, 16, v42
	v_lshlrev_b32_e32 v45, 16, v45
	v_lshlrev_b32_e32 v44, 16, v44
	s_nop 0
	s_nop 0
	s_nop 0
	s_nop 0
	s_nop 0
	s_nop 0
	s_nop 0
	s_nop 0
	s_nop 0
	s_nop 0
	s_nop 0
	s_nop 0
	s_nop 0
	s_add_i32 s7, s38, 32
	s_cmpk_gt_i32 s38, 0xffdf
	s_cselect_b64 s[18:19], -1, 0
	s_cmp_lt_i32 s7, s6
	s_cselect_b64 s[20:21], -1, 0
	s_and_b64 s[18:19], s[18:19], s[20:21]
	s_andn2_b64 vcc, exec, s[18:19]
	v_mov_b32_e32 v46, 0
	s_cbranch_vccnz .LBB0_618
	v_mad_u64_u32 v[2:3], s[6:7], s7, v202, v[2:3]
	flat_load_ushort v2, v[2:3]
	s_waitcnt vmcnt(0) lgkmcnt(0)
	v_lshlrev_b32_e32 v46, 16, v2

; #define LDX(tt) (((tt) >= 0 && (tt) < seqlen) ? bf1(xp[(size_t)(tt) * INP]) : 0.f)
; #define LDX(tt) (((tt) >= 0 && (tt) < seqlen) ? bf1(xp[(size_t)(tt) * INP]) : 0.f)
; template <bool PASS2> ...
;     ...
;     const int blk = t & 3, c = (t >> 2) % NCH, b = (t >> 2) / NCH;
;     const int seqlen = c < 8 ? 256 : 2048, t0 = c < 8 ? c * 32 : (c - 8) * 32, rbase = c < 8 ? ML + b * 256 : b * 2048;
;     bf16x8 af[2][2];
;     if (!PASS2) {
;         const int ch = blk * 64 + lane;
;         const float w0 = convw[(l * 4 + 0) * 256 + ch], w1 = convw[(l * 4 + 1) * 256 + ch], w2 = convw[(l * 4 + 2) * 256 + ch], w3 = convw[(l * 4 + 3) * 256 + ch], cb = convb[l * 256 + ch];
;         const bf16_t* xp = P + (size_t)rbase * INP + OFF_LRU + ch;
;     ...
;         float xs[35];
; #pragma unroll
;         for (int s = 0; s < 35; ++s) xs[s] = LDX(t0 + s - 2);
.LBB0_667:
	s_ashr_i32 s4, s23, 2
	s_mul_hi_i32 s1, s4, 0x38e38e39
	s_lshr_b32 s5, s1, 31
	s_ashr_i32 s1, s1, 4
	s_add_i32 s1, s1, s5
	s_mul_i32 s5, s1, 0x48
	s_sub_i32 s5, s4, s5
	s_lshl_b32 s7, s5, 5
	s_lshl_b32 s6, s1, 8
	s_add_i32 s14, s7, 0xffffff00
	s_add_i32 s15, s6, 0x4000
	s_lshl_b32 s1, s1, 11
	s_cmp_lt_i32 s5, 8
	s_movk_i32 s5, 0x800
	s_cselect_b32 s6, 0x100, s5
	s_cselect_b32 s38, s7, s14
	s_cselect_b32 s1, s15, s1
	s_lshl_b32 s5, s23, 6
	s_and_b32 s5, s5, 0xc0
	v_or_b32_e32 v9, s5, v95
	v_readlane_b32 s7, v254, 32
	v_readlane_b32 s48, v251, 24
	v_readlane_b32 s49, v251, 25
	s_waitcnt lgkmcnt(0)
	v_or_b32_e32 v0, s7, v9
	v_readlane_b32 s50, v251, 26
	v_readlane_b32 s51, v251, 27
	v_readlane_b32 s52, v251, 28
	v_readlane_b32 s53, v251, 29
	v_readlane_b32 s54, v251, 30
	v_readlane_b32 s55, v251, 31
	v_readlane_b32 s56, v251, 32
	v_readlane_b32 s57, v251, 33
	v_readlane_b32 s58, v251, 34
	v_readlane_b32 s59, v251, 35
	v_readlane_b32 s60, v251, 36
	v_readlane_b32 s61, v251, 37
	v_readlane_b32 s62, v251, 38
	v_readlane_b32 s63, v251, 39
	v_readlane_b32 s14, v254, 21
	s_mul_hi_i32 s7, s1, 0x2200
	v_lshl_add_u64 v[2:3], v[0:1], 2, s[62:63]
	v_readlane_b32 s48, v251, 40
	global_load_dword v7, v[2:3], off
	global_load_dword v6, v[2:3], off offset:1024
	global_load_dword v5, v[2:3], off offset:2048
	global_load_dword v4, v[2:3], off offset:3072
	v_or_b32_e32 v0, s14, v9
	v_readlane_b32 s49, v251, 41
	s_mul_i32 s14, s1, 0x2200
	s_add_u32 s18, s40, s14
	v_lshl_add_u64 v[2:3], v[0:1], 2, s[48:49]
	global_load_dword v8, v[2:3], off
	s_addc_u32 s19, s41, s7
	v_lshlrev_b32_e32 v0, 1, v9
	s_cmp_lt_i32 s38, 2
	v_lshl_add_u64 v[2:3], s[18:19], 0, v[0:1]
	s_cselect_b64 s[18:19], -1, 0
	s_cmp_le_i32 s38, s6
	s_cselect_b64 s[20:21], -1, 0
	s_cmp_gt_i32 s38, s6
	v_readlane_b32 s15, v254, 22
	s_cselect_b64 s[24:25], -1, 0
	s_mov_b64 s[14:15], 0x8eb8340
	s_or_b64 s[18:19], s[18:19], s[24:25]
	v_lshl_add_u64 v[2:3], v[2:3], 0, s[14:15]
	v_mov_b32_e32 v0, 0
	s_and_b64 vcc, exec, s[18:19]
	v_mov_b32_e32 v9, 0
	v_readlane_b32 s50, v251, 42
	v_readlane_b32 s51, v251, 43
	v_readlane_b32 s52, v251, 44
	v_readlane_b32 s53, v251, 45
	v_readlane_b32 s54, v251, 46
	v_readlane_b32 s55, v251, 47
	v_readlane_b32 s56, v251, 48
	v_readlane_b32 s57, v251, 49
	v_readlane_b32 s58, v251, 50
	v_readlane_b32 s59, v251, 51
	v_readlane_b32 s60, v251, 52
	v_readlane_b32 s61, v251, 53
	v_readlane_b32 s62, v251, 54
	v_readlane_b32 s63, v251, 55
	s_cbranch_vccnz .LBB0_669
	s_add_i32 s7, s38, -2
	v_mad_u64_u32 v[14:15], s[18:19], s7, v202, v[2:3]
	flat_load_ushort v9, v[14:15]
	s_nop 0
	s_nop 0
